# next-head u-row requests issued after the GELU (start of the fp4 block) instead of before the butterfly
# baseline (speedup 1.0000x reference)
.LBB0_329:
	s_or_b64 exec, exec, s[2:3]
	v_add_u32_e32 v254, s24, v239
	ds_read_b32 v12, v254 offset:512
	s_waitcnt lgkmcnt(0)
	ds_bpermute_b32 v0, v255, v12
	ds_bpermute_b32 v2, v255, v12 offset:16
	ds_bpermute_b32 v3, v255, v12 offset:32
	ds_bpermute_b32 v6, v255, v12 offset:48
	ds_bpermute_b32 v7, v255, v12 offset:64
	ds_bpermute_b32 v10, v255, v12 offset:80
	ds_bpermute_b32 v11, v255, v12 offset:96
	ds_bpermute_b32 v14, v255, v12 offset:112
	s_waitcnt lgkmcnt(7)
	v_mad_i64_i32 v[22:23], s[2:3], v0, s28, v[118:119]
	global_load_dwordx2 v[36:37], v[22:23], off offset:16
	global_load_dwordx4 v[32:35], v[22:23], off
	s_waitcnt lgkmcnt(6)
	v_mad_i64_i32 v[24:25], s[2:3], v2, s28, v[118:119]
	global_load_dwordx2 v[42:43], v[24:25], off offset:16
	global_load_dwordx4 v[38:41], v[24:25], off
	s_waitcnt lgkmcnt(5)
	v_mad_i64_i32 v[22:23], s[2:3], v3, s28, v[118:119]
	global_load_dwordx2 v[48:49], v[22:23], off offset:16
	global_load_dwordx4 v[44:47], v[22:23], off
	s_waitcnt lgkmcnt(4)
	v_mad_i64_i32 v[24:25], s[2:3], v6, s28, v[118:119]
	global_load_dwordx2 v[54:55], v[24:25], off offset:16
	global_load_dwordx4 v[50:53], v[24:25], off
	s_waitcnt lgkmcnt(3)
	v_mad_i64_i32 v[22:23], s[2:3], v7, s28, v[118:119]
	global_load_dwordx2 v[60:61], v[22:23], off offset:16
	global_load_dwordx4 v[56:59], v[22:23], off
	s_waitcnt lgkmcnt(2)
	v_mad_i64_i32 v[24:25], s[2:3], v10, s28, v[118:119]
	global_load_dwordx2 v[66:67], v[24:25], off offset:16
	global_load_dwordx4 v[62:65], v[24:25], off
	s_waitcnt lgkmcnt(1)
	v_mad_i64_i32 v[22:23], s[2:3], v11, s28, v[118:119]
	global_load_dwordx2 v[72:73], v[22:23], off offset:16
	global_load_dwordx4 v[68:71], v[22:23], off
	s_waitcnt lgkmcnt(0)
	v_mad_i64_i32 v[24:25], s[2:3], v14, s28, v[118:119]
	global_load_dwordx2 v[78:79], v[24:25], off offset:16
	global_load_dwordx4 v[74:77], v[24:25], off
	v_mad_i64_i32 v[0:1], s[2:3], v0, s28, 0
	v_mad_i64_i32 v[4:5], s[2:3], v2, s28, 0
	v_mad_i64_i32 v[2:3], s[2:3], v3, s28, 0
	v_mad_i64_i32 v[8:9], s[2:3], v6, s28, 0
	v_mad_i64_i32 v[6:7], s[2:3], v7, s28, 0
	v_mad_i64_i32 v[12:13], s[2:3], v10, s28, 0
	v_mad_i64_i32 v[10:11], s[2:3], v11, s28, 0
	v_mad_i64_i32 v[14:15], s[2:3], v14, s28, 0
	s_brev_b32 s2, -2
	s_nop 0
	v_bfi_b32 v16, s2, v19, v16
	v_mul_f32_e32 v18, 0.5, v18
	v_add_f32_e32 v16, 1.0, v16
	v_mul_f32_e32 v16, v18, v16
	v_mul_f32_e32 v16, v17, v16
	v_mul_f32_e32 v117, 0x3daaaaab, v16
	ds_bpermute_b32 v250, v255, v117
	s_nop 0
	s_waitcnt vmcnt(23)
	v_cvt_scalef32_pk_f32_fp4 v[18:19], v110, 1.0
	s_waitcnt lgkmcnt(0)
	ds_bpermute_b32 v252, v255, v117 offset:16
	v_cvt_scalef32_pk_f32_fp4 v[20:21], v110, 1.0 op_sel:[1,0,0]
	v_cvt_scalef32_pk_f32_fp4 v[22:23], v110, 1.0 op_sel:[0,1,0]
	v_cvt_scalef32_pk_f32_fp4 v[24:25], v110, 1.0 op_sel:[1,1,0]
	v_cvt_scalef32_pk_f32_fp4 v[26:27], v111, 1.0
	v_cvt_scalef32_pk_f32_fp4 v[28:29], v111, 1.0 op_sel:[1,0,0]
	v_cvt_scalef32_pk_f32_fp4 v[30:31], v111, 1.0 op_sel:[0,1,0]
	v_cvt_scalef32_pk_f32_fp4 v[110:111], v111, 1.0 op_sel:[1,1,0]
	v_pk_fma_f32 v[110:111], v[250:251], v[110:111], v[202:203] op_sel_hi:[0,1,1]
	v_cvt_scalef32_pk_f32_fp4 v[202:203], v112, 1.0
	v_pk_fma_f32 v[200:201], v[250:251], v[202:203], v[200:201] op_sel_hi:[0,1,1]
	v_cvt_scalef32_pk_f32_fp4 v[202:203], v112, 1.0 op_sel:[1,0,0]
	v_pk_fma_f32 v[198:199], v[250:251], v[202:203], v[198:199] op_sel_hi:[0,1,1]
	v_cvt_scalef32_pk_f32_fp4 v[202:203], v112, 1.0 op_sel:[0,1,0]
	v_pk_fma_f32 v[196:197], v[250:251], v[202:203], v[196:197] op_sel_hi:[0,1,1]
	v_cvt_scalef32_pk_f32_fp4 v[202:203], v112, 1.0 op_sel:[1,1,0]
	v_pk_fma_f32 v[194:195], v[250:251], v[202:203], v[194:195] op_sel_hi:[0,1,1]
	v_cvt_scalef32_pk_f32_fp4 v[202:203], v113, 1.0
	v_pk_fma_f32 v[192:193], v[250:251], v[202:203], v[192:193] op_sel_hi:[0,1,1]
	v_cvt_scalef32_pk_f32_fp4 v[202:203], v113, 1.0 op_sel:[1,0,0]
	v_pk_fma_f32 v[190:191], v[250:251], v[202:203], v[190:191] op_sel_hi:[0,1,1]
	v_cvt_scalef32_pk_f32_fp4 v[202:203], v113, 1.0 op_sel:[0,1,0]
	v_pk_fma_f32 v[188:189], v[250:251], v[202:203], v[188:189] op_sel_hi:[0,1,1]
	v_cvt_scalef32_pk_f32_fp4 v[112:113], v113, 1.0 op_sel:[1,1,0]
	v_pk_fma_f32 v[18:19], v[18:19], v[250:251], v[216:217] op_sel_hi:[1,0,1]
	v_pk_fma_f32 v[20:21], v[20:21], v[250:251], v[214:215] op_sel_hi:[1,0,1]
	v_pk_fma_f32 v[22:23], v[22:23], v[250:251], v[212:213] op_sel_hi:[1,0,1]
	v_pk_fma_f32 v[24:25], v[250:251], v[24:25], v[210:211] op_sel_hi:[0,1,1]
	v_pk_fma_f32 v[26:27], v[250:251], v[26:27], v[208:209] op_sel_hi:[0,1,1]
	v_pk_fma_f32 v[28:29], v[250:251], v[28:29], v[206:207] op_sel_hi:[0,1,1]
	v_pk_fma_f32 v[30:31], v[250:251], v[30:31], v[204:205] op_sel_hi:[0,1,1]
	v_pk_fma_f32 v[16:17], v[250:251], v[112:113], v[176:177] op_sel_hi:[0,1,1]
	s_waitcnt vmcnt(22)
	v_cvt_scalef32_pk_f32_fp4 v[176:177], v106, 1.0
	s_waitcnt lgkmcnt(0)
	ds_bpermute_b32 v250, v255, v117 offset:32
	v_pk_fma_f32 v[18:19], v[176:177], v[252:253], v[18:19] op_sel_hi:[1,0,1]
	v_cvt_scalef32_pk_f32_fp4 v[176:177], v106, 1.0 op_sel:[1,0,0]
	v_pk_fma_f32 v[20:21], v[176:177], v[252:253], v[20:21] op_sel_hi:[1,0,1]
	v_cvt_scalef32_pk_f32_fp4 v[176:177], v106, 1.0 op_sel:[0,1,0]
	v_pk_fma_f32 v[22:23], v[176:177], v[252:253], v[22:23] op_sel_hi:[1,0,1]
	v_cvt_scalef32_pk_f32_fp4 v[176:177], v106, 1.0 op_sel:[1,1,0]
	v_pk_fma_f32 v[24:25], v[252:253], v[176:177], v[24:25] op_sel_hi:[0,1,1]
	v_cvt_scalef32_pk_f32_fp4 v[176:177], v107, 1.0
	v_pk_fma_f32 v[26:27], v[252:253], v[176:177], v[26:27] op_sel_hi:[0,1,1]
	v_cvt_scalef32_pk_f32_fp4 v[176:177], v107, 1.0 op_sel:[1,0,0]
	v_pk_fma_f32 v[28:29], v[252:253], v[176:177], v[28:29] op_sel_hi:[0,1,1]
	v_cvt_scalef32_pk_f32_fp4 v[176:177], v107, 1.0 op_sel:[0,1,0]
	v_pk_fma_f32 v[30:31], v[252:253], v[176:177], v[30:31] op_sel_hi:[0,1,1]
	v_cvt_scalef32_pk_f32_fp4 v[176:177], v108, 1.0 op_sel:[1,0,0]
	v_pk_fma_f32 v[176:177], v[252:253], v[176:177], v[198:199] op_sel_hi:[0,1,1]
	v_cvt_scalef32_pk_f32_fp4 v[198:199], v108, 1.0 op_sel:[0,1,0]
	v_pk_fma_f32 v[196:197], v[252:253], v[198:199], v[196:197] op_sel_hi:[0,1,1]
	v_cvt_scalef32_pk_f32_fp4 v[198:199], v108, 1.0 op_sel:[1,1,0]
	v_pk_fma_f32 v[194:195], v[252:253], v[198:199], v[194:195] op_sel_hi:[0,1,1]
	v_cvt_scalef32_pk_f32_fp4 v[198:199], v109, 1.0
	v_cvt_scalef32_pk_f32_fp4 v[106:107], v107, 1.0 op_sel:[1,1,0]
	v_pk_fma_f32 v[192:193], v[252:253], v[198:199], v[192:193] op_sel_hi:[0,1,1]
	v_cvt_scalef32_pk_f32_fp4 v[198:199], v109, 1.0 op_sel:[1,0,0]
	v_pk_fma_f32 v[106:107], v[252:253], v[106:107], v[110:111] op_sel_hi:[0,1,1]
	v_cvt_scalef32_pk_f32_fp4 v[110:111], v108, 1.0
	v_pk_fma_f32 v[190:191], v[252:253], v[198:199], v[190:191] op_sel_hi:[0,1,1]
	v_cvt_scalef32_pk_f32_fp4 v[198:199], v109, 1.0 op_sel:[0,1,0]
	v_pk_fma_f32 v[110:111], v[252:253], v[110:111], v[200:201] op_sel_hi:[0,1,1]
	v_pk_fma_f32 v[188:189], v[252:253], v[198:199], v[188:189] op_sel_hi:[0,1,1]
	v_cvt_scalef32_pk_f32_fp4 v[108:109], v109, 1.0 op_sel:[1,1,0]
	v_pk_fma_f32 v[16:17], v[252:253], v[108:109], v[16:17] op_sel_hi:[0,1,1]
	s_waitcnt vmcnt(21)
	v_cvt_scalef32_pk_f32_fp4 v[112:113], v102, 1.0
	s_waitcnt lgkmcnt(0)
	ds_bpermute_b32 v252, v255, v117 offset:48
	v_pk_fma_f32 v[18:19], v[112:113], v[250:251], v[18:19] op_sel_hi:[1,0,1]
	v_cvt_scalef32_pk_f32_fp4 v[112:113], v102, 1.0 op_sel:[1,0,0]
	v_pk_fma_f32 v[20:21], v[112:113], v[250:251], v[20:21] op_sel_hi:[1,0,1]
	v_cvt_scalef32_pk_f32_fp4 v[112:113], v102, 1.0 op_sel:[0,1,0]
	v_pk_fma_f32 v[22:23], v[112:113], v[250:251], v[22:23] op_sel_hi:[1,0,1]
	v_cvt_scalef32_pk_f32_fp4 v[112:113], v102, 1.0 op_sel:[1,1,0]
	v_pk_fma_f32 v[24:25], v[250:251], v[112:113], v[24:25] op_sel_hi:[0,1,1]
	v_cvt_scalef32_pk_f32_fp4 v[112:113], v103, 1.0
	v_pk_fma_f32 v[26:27], v[250:251], v[112:113], v[26:27] op_sel_hi:[0,1,1]
	v_cvt_scalef32_pk_f32_fp4 v[112:113], v103, 1.0 op_sel:[1,0,0]
	v_pk_fma_f32 v[28:29], v[250:251], v[112:113], v[28:29] op_sel_hi:[0,1,1]
	v_cvt_scalef32_pk_f32_fp4 v[112:113], v103, 1.0 op_sel:[0,1,0]
	v_cvt_scalef32_pk_f32_fp4 v[102:103], v103, 1.0 op_sel:[1,1,0]
	v_pk_fma_f32 v[102:103], v[250:251], v[102:103], v[106:107] op_sel_hi:[0,1,1]
	v_cvt_scalef32_pk_f32_fp4 v[106:107], v104, 1.0
	v_pk_fma_f32 v[106:107], v[250:251], v[106:107], v[110:111] op_sel_hi:[0,1,1]
	v_cvt_scalef32_pk_f32_fp4 v[110:111], v104, 1.0 op_sel:[1,0,0]
	v_pk_fma_f32 v[110:111], v[250:251], v[110:111], v[176:177] op_sel_hi:[0,1,1]
	v_cvt_scalef32_pk_f32_fp4 v[176:177], v104, 1.0 op_sel:[1,1,0]
	v_pk_fma_f32 v[176:177], v[250:251], v[176:177], v[194:195] op_sel_hi:[0,1,1]
	v_cvt_scalef32_pk_f32_fp4 v[194:195], v105, 1.0
	v_pk_fma_f32 v[192:193], v[250:251], v[194:195], v[192:193] op_sel_hi:[0,1,1]
	v_cvt_scalef32_pk_f32_fp4 v[194:195], v105, 1.0 op_sel:[1,0,0]
	v_pk_fma_f32 v[30:31], v[250:251], v[112:113], v[30:31] op_sel_hi:[0,1,1]
	v_cvt_scalef32_pk_f32_fp4 v[112:113], v104, 1.0 op_sel:[0,1,0]
	v_pk_fma_f32 v[190:191], v[250:251], v[194:195], v[190:191] op_sel_hi:[0,1,1]
	v_cvt_scalef32_pk_f32_fp4 v[194:195], v105, 1.0 op_sel:[0,1,0]
	v_pk_fma_f32 v[112:113], v[250:251], v[112:113], v[196:197] op_sel_hi:[0,1,1]
	v_pk_fma_f32 v[188:189], v[250:251], v[194:195], v[188:189] op_sel_hi:[0,1,1]
	v_cvt_scalef32_pk_f32_fp4 v[104:105], v105, 1.0 op_sel:[1,1,0]
	v_pk_fma_f32 v[16:17], v[250:251], v[104:105], v[16:17] op_sel_hi:[0,1,1]
	s_waitcnt vmcnt(20)
	v_cvt_scalef32_pk_f32_fp4 v[108:109], v98, 1.0
	s_waitcnt lgkmcnt(0)
	ds_bpermute_b32 v250, v255, v117 offset:64
	v_pk_fma_f32 v[18:19], v[108:109], v[252:253], v[18:19] op_sel_hi:[1,0,1]
	v_cvt_scalef32_pk_f32_fp4 v[108:109], v98, 1.0 op_sel:[1,0,0]
	v_pk_fma_f32 v[20:21], v[108:109], v[252:253], v[20:21] op_sel_hi:[1,0,1]
	v_cvt_scalef32_pk_f32_fp4 v[108:109], v98, 1.0 op_sel:[0,1,0]
	v_pk_fma_f32 v[22:23], v[108:109], v[252:253], v[22:23] op_sel_hi:[1,0,1]
	v_cvt_scalef32_pk_f32_fp4 v[108:109], v98, 1.0 op_sel:[1,1,0]
	v_pk_fma_f32 v[24:25], v[252:253], v[108:109], v[24:25] op_sel_hi:[0,1,1]
	v_cvt_scalef32_pk_f32_fp4 v[108:109], v99, 1.0
	v_pk_fma_f32 v[26:27], v[252:253], v[108:109], v[26:27] op_sel_hi:[0,1,1]
	v_cvt_scalef32_pk_f32_fp4 v[108:109], v99, 1.0 op_sel:[1,0,0]
	v_pk_fma_f32 v[28:29], v[252:253], v[108:109], v[28:29] op_sel_hi:[0,1,1]
	v_cvt_scalef32_pk_f32_fp4 v[108:109], v99, 1.0 op_sel:[0,1,0]
	v_cvt_scalef32_pk_f32_fp4 v[98:99], v99, 1.0 op_sel:[1,1,0]
	v_pk_fma_f32 v[98:99], v[252:253], v[98:99], v[102:103] op_sel_hi:[0,1,1]
	v_cvt_scalef32_pk_f32_fp4 v[102:103], v100, 1.0
	v_pk_fma_f32 v[102:103], v[252:253], v[102:103], v[106:107] op_sel_hi:[0,1,1]
	v_cvt_scalef32_pk_f32_fp4 v[106:107], v100, 1.0 op_sel:[1,0,0]
	v_pk_fma_f32 v[106:107], v[252:253], v[106:107], v[110:111] op_sel_hi:[0,1,1]
	v_cvt_scalef32_pk_f32_fp4 v[110:111], v100, 1.0 op_sel:[1,1,0]
	v_pk_fma_f32 v[30:31], v[252:253], v[108:109], v[30:31] op_sel_hi:[0,1,1]
	v_cvt_scalef32_pk_f32_fp4 v[108:109], v100, 1.0 op_sel:[0,1,0]
	v_pk_fma_f32 v[110:111], v[252:253], v[110:111], v[176:177] op_sel_hi:[0,1,1]
	v_cvt_scalef32_pk_f32_fp4 v[176:177], v101, 1.0 op_sel:[1,0,0]
	v_pk_fma_f32 v[108:109], v[252:253], v[108:109], v[112:113] op_sel_hi:[0,1,1]
	v_cvt_scalef32_pk_f32_fp4 v[112:113], v101, 1.0
	v_pk_fma_f32 v[176:177], v[252:253], v[176:177], v[190:191] op_sel_hi:[0,1,1]
	v_cvt_scalef32_pk_f32_fp4 v[190:191], v101, 1.0 op_sel:[0,1,0]
	v_pk_fma_f32 v[112:113], v[252:253], v[112:113], v[192:193] op_sel_hi:[0,1,1]
	v_pk_fma_f32 v[188:189], v[252:253], v[190:191], v[188:189] op_sel_hi:[0,1,1]
	v_cvt_scalef32_pk_f32_fp4 v[100:101], v101, 1.0 op_sel:[1,1,0]
	v_pk_fma_f32 v[16:17], v[252:253], v[100:101], v[16:17] op_sel_hi:[0,1,1]
	s_waitcnt vmcnt(19)
	v_cvt_scalef32_pk_f32_fp4 v[104:105], v94, 1.0
	s_waitcnt lgkmcnt(0)
	ds_bpermute_b32 v252, v255, v117 offset:80
	v_pk_fma_f32 v[18:19], v[104:105], v[250:251], v[18:19] op_sel_hi:[1,0,1]
	v_cvt_scalef32_pk_f32_fp4 v[104:105], v94, 1.0 op_sel:[1,0,0]
	v_pk_fma_f32 v[20:21], v[104:105], v[250:251], v[20:21] op_sel_hi:[1,0,1]
	v_cvt_scalef32_pk_f32_fp4 v[104:105], v94, 1.0 op_sel:[0,1,0]
	v_pk_fma_f32 v[22:23], v[104:105], v[250:251], v[22:23] op_sel_hi:[1,0,1]
	v_cvt_scalef32_pk_f32_fp4 v[104:105], v94, 1.0 op_sel:[1,1,0]
	v_pk_fma_f32 v[24:25], v[250:251], v[104:105], v[24:25] op_sel_hi:[0,1,1]
	v_cvt_scalef32_pk_f32_fp4 v[104:105], v95, 1.0
	v_pk_fma_f32 v[26:27], v[250:251], v[104:105], v[26:27] op_sel_hi:[0,1,1]
	v_cvt_scalef32_pk_f32_fp4 v[104:105], v95, 1.0 op_sel:[1,0,0]
	v_pk_fma_f32 v[28:29], v[250:251], v[104:105], v[28:29] op_sel_hi:[0,1,1]
	v_cvt_scalef32_pk_f32_fp4 v[104:105], v95, 1.0 op_sel:[0,1,0]
	v_cvt_scalef32_pk_f32_fp4 v[94:95], v95, 1.0 op_sel:[1,1,0]
	v_pk_fma_f32 v[94:95], v[250:251], v[94:95], v[98:99] op_sel_hi:[0,1,1]
	v_cvt_scalef32_pk_f32_fp4 v[98:99], v96, 1.0
	v_pk_fma_f32 v[30:31], v[250:251], v[104:105], v[30:31] op_sel_hi:[0,1,1]
	v_pk_fma_f32 v[98:99], v[250:251], v[98:99], v[102:103] op_sel_hi:[0,1,1]
	v_cvt_scalef32_pk_f32_fp4 v[102:103], v96, 1.0 op_sel:[1,0,0]
	v_cvt_scalef32_pk_f32_fp4 v[104:105], v96, 1.0 op_sel:[0,1,0]
	v_pk_fma_f32 v[102:103], v[250:251], v[102:103], v[106:107] op_sel_hi:[0,1,1]
	v_pk_fma_f32 v[104:105], v[250:251], v[104:105], v[108:109] op_sel_hi:[0,1,1]
	v_cvt_scalef32_pk_f32_fp4 v[106:107], v96, 1.0 op_sel:[1,1,0]
	v_cvt_scalef32_pk_f32_fp4 v[108:109], v97, 1.0
	v_pk_fma_f32 v[106:107], v[250:251], v[106:107], v[110:111] op_sel_hi:[0,1,1]
	v_pk_fma_f32 v[108:109], v[250:251], v[108:109], v[112:113] op_sel_hi:[0,1,1]
	v_cvt_scalef32_pk_f32_fp4 v[110:111], v97, 1.0 op_sel:[1,0,0]
	v_cvt_scalef32_pk_f32_fp4 v[112:113], v97, 1.0 op_sel:[0,1,0]
	v_pk_fma_f32 v[110:111], v[250:251], v[110:111], v[176:177] op_sel_hi:[0,1,1]
	v_pk_fma_f32 v[112:113], v[250:251], v[112:113], v[188:189] op_sel_hi:[0,1,1]
	v_cvt_scalef32_pk_f32_fp4 v[96:97], v97, 1.0 op_sel:[1,1,0]
	v_pk_fma_f32 v[16:17], v[250:251], v[96:97], v[16:17] op_sel_hi:[0,1,1]
	s_waitcnt vmcnt(18)
	v_cvt_scalef32_pk_f32_fp4 v[100:101], v90, 1.0
	s_waitcnt lgkmcnt(0)
	ds_bpermute_b32 v250, v255, v117 offset:96
	v_pk_fma_f32 v[18:19], v[100:101], v[252:253], v[18:19] op_sel_hi:[1,0,1]
	v_cvt_scalef32_pk_f32_fp4 v[100:101], v90, 1.0 op_sel:[1,0,0]
	v_pk_fma_f32 v[20:21], v[100:101], v[252:253], v[20:21] op_sel_hi:[1,0,1]
	v_cvt_scalef32_pk_f32_fp4 v[100:101], v90, 1.0 op_sel:[0,1,0]
	v_pk_fma_f32 v[22:23], v[100:101], v[252:253], v[22:23] op_sel_hi:[1,0,1]
	v_cvt_scalef32_pk_f32_fp4 v[100:101], v90, 1.0 op_sel:[1,1,0]
	v_pk_fma_f32 v[24:25], v[252:253], v[100:101], v[24:25] op_sel_hi:[0,1,1]
	v_cvt_scalef32_pk_f32_fp4 v[100:101], v91, 1.0
	v_pk_fma_f32 v[26:27], v[252:253], v[100:101], v[26:27] op_sel_hi:[0,1,1]
	v_cvt_scalef32_pk_f32_fp4 v[100:101], v91, 1.0 op_sel:[1,0,0]
	v_pk_fma_f32 v[28:29], v[252:253], v[100:101], v[28:29] op_sel_hi:[0,1,1]
	v_cvt_scalef32_pk_f32_fp4 v[100:101], v91, 1.0 op_sel:[0,1,0]
	v_cvt_scalef32_pk_f32_fp4 v[90:91], v91, 1.0 op_sel:[1,1,0]
	v_pk_fma_f32 v[90:91], v[252:253], v[90:91], v[94:95] op_sel_hi:[0,1,1]
	v_cvt_scalef32_pk_f32_fp4 v[94:95], v92, 1.0
	v_pk_fma_f32 v[30:31], v[252:253], v[100:101], v[30:31] op_sel_hi:[0,1,1]
	v_pk_fma_f32 v[94:95], v[252:253], v[94:95], v[98:99] op_sel_hi:[0,1,1]
	v_cvt_scalef32_pk_f32_fp4 v[98:99], v92, 1.0 op_sel:[1,0,0]
	v_cvt_scalef32_pk_f32_fp4 v[100:101], v92, 1.0 op_sel:[0,1,0]
	v_pk_fma_f32 v[98:99], v[252:253], v[98:99], v[102:103] op_sel_hi:[0,1,1]
	v_pk_fma_f32 v[100:101], v[252:253], v[100:101], v[104:105] op_sel_hi:[0,1,1]
	v_cvt_scalef32_pk_f32_fp4 v[102:103], v92, 1.0 op_sel:[1,1,0]
	v_cvt_scalef32_pk_f32_fp4 v[104:105], v93, 1.0
	v_pk_fma_f32 v[102:103], v[252:253], v[102:103], v[106:107] op_sel_hi:[0,1,1]
	v_pk_fma_f32 v[104:105], v[252:253], v[104:105], v[108:109] op_sel_hi:[0,1,1]
	v_cvt_scalef32_pk_f32_fp4 v[106:107], v93, 1.0 op_sel:[1,0,0]
	v_cvt_scalef32_pk_f32_fp4 v[108:109], v93, 1.0 op_sel:[0,1,0]
	v_pk_fma_f32 v[106:107], v[252:253], v[106:107], v[110:111] op_sel_hi:[0,1,1]
	v_pk_fma_f32 v[108:109], v[252:253], v[108:109], v[112:113] op_sel_hi:[0,1,1]
	v_cvt_scalef32_pk_f32_fp4 v[92:93], v93, 1.0 op_sel:[1,1,0]
	v_pk_fma_f32 v[16:17], v[252:253], v[92:93], v[16:17] op_sel_hi:[0,1,1]
	s_waitcnt vmcnt(17)
	v_cvt_scalef32_pk_f32_fp4 v[96:97], v86, 1.0
	s_waitcnt lgkmcnt(0)
	ds_bpermute_b32 v252, v255, v117 offset:112
	v_pk_fma_f32 v[18:19], v[96:97], v[250:251], v[18:19] op_sel_hi:[1,0,1]
	v_cvt_scalef32_pk_f32_fp4 v[96:97], v86, 1.0 op_sel:[1,0,0]
	v_pk_fma_f32 v[20:21], v[96:97], v[250:251], v[20:21] op_sel_hi:[1,0,1]
	v_cvt_scalef32_pk_f32_fp4 v[96:97], v86, 1.0 op_sel:[0,1,0]
	v_pk_fma_f32 v[22:23], v[96:97], v[250:251], v[22:23] op_sel_hi:[1,0,1]
	v_cvt_scalef32_pk_f32_fp4 v[96:97], v86, 1.0 op_sel:[1,1,0]
	v_pk_fma_f32 v[24:25], v[250:251], v[96:97], v[24:25] op_sel_hi:[0,1,1]
	v_cvt_scalef32_pk_f32_fp4 v[96:97], v87, 1.0
	v_pk_fma_f32 v[26:27], v[250:251], v[96:97], v[26:27] op_sel_hi:[0,1,1]
	v_cvt_scalef32_pk_f32_fp4 v[96:97], v87, 1.0 op_sel:[1,0,0]
	v_pk_fma_f32 v[28:29], v[250:251], v[96:97], v[28:29] op_sel_hi:[0,1,1]
	v_cvt_scalef32_pk_f32_fp4 v[96:97], v87, 1.0 op_sel:[0,1,0]
	v_cvt_scalef32_pk_f32_fp4 v[86:87], v87, 1.0 op_sel:[1,1,0]
	v_pk_fma_f32 v[86:87], v[250:251], v[86:87], v[90:91] op_sel_hi:[0,1,1]
	v_cvt_scalef32_pk_f32_fp4 v[90:91], v88, 1.0
	v_pk_fma_f32 v[30:31], v[250:251], v[96:97], v[30:31] op_sel_hi:[0,1,1]
	v_pk_fma_f32 v[90:91], v[250:251], v[90:91], v[94:95] op_sel_hi:[0,1,1]
	v_cvt_scalef32_pk_f32_fp4 v[94:95], v88, 1.0 op_sel:[1,0,0]
	v_cvt_scalef32_pk_f32_fp4 v[96:97], v88, 1.0 op_sel:[0,1,0]
	v_pk_fma_f32 v[94:95], v[250:251], v[94:95], v[98:99] op_sel_hi:[0,1,1]
	v_pk_fma_f32 v[96:97], v[250:251], v[96:97], v[100:101] op_sel_hi:[0,1,1]
	v_cvt_scalef32_pk_f32_fp4 v[98:99], v88, 1.0 op_sel:[1,1,0]
	v_cvt_scalef32_pk_f32_fp4 v[100:101], v89, 1.0
	v_pk_fma_f32 v[98:99], v[250:251], v[98:99], v[102:103] op_sel_hi:[0,1,1]
	v_pk_fma_f32 v[100:101], v[250:251], v[100:101], v[104:105] op_sel_hi:[0,1,1]
	v_cvt_scalef32_pk_f32_fp4 v[102:103], v89, 1.0 op_sel:[1,0,0]
	v_cvt_scalef32_pk_f32_fp4 v[104:105], v89, 1.0 op_sel:[0,1,0]
	v_pk_fma_f32 v[102:103], v[250:251], v[102:103], v[106:107] op_sel_hi:[0,1,1]
	v_pk_fma_f32 v[104:105], v[250:251], v[104:105], v[108:109] op_sel_hi:[0,1,1]
	v_cvt_scalef32_pk_f32_fp4 v[88:89], v89, 1.0 op_sel:[1,1,0]
	v_pk_fma_f32 v[16:17], v[250:251], v[88:89], v[16:17] op_sel_hi:[0,1,1]
	s_waitcnt vmcnt(16)
	v_cvt_scalef32_pk_f32_fp4 v[92:93], v82, 1.0
	s_waitcnt lgkmcnt(0)
	v_pk_fma_f32 v[216:217], v[92:93], v[252:253], v[18:19] op_sel_hi:[1,0,1]
	v_cvt_scalef32_pk_f32_fp4 v[18:19], v82, 1.0 op_sel:[1,0,0]
	v_pk_fma_f32 v[214:215], v[18:19], v[252:253], v[20:21] op_sel_hi:[1,0,1]
	v_cvt_scalef32_pk_f32_fp4 v[18:19], v82, 1.0 op_sel:[0,1,0]
	v_pk_fma_f32 v[212:213], v[18:19], v[252:253], v[22:23] op_sel_hi:[1,0,1]
	v_cvt_scalef32_pk_f32_fp4 v[18:19], v82, 1.0 op_sel:[1,1,0]
	v_pk_fma_f32 v[210:211], v[252:253], v[18:19], v[24:25] op_sel_hi:[0,1,1]
	v_cvt_scalef32_pk_f32_fp4 v[18:19], v83, 1.0
	v_pk_fma_f32 v[208:209], v[252:253], v[18:19], v[26:27] op_sel_hi:[0,1,1]
	v_cvt_scalef32_pk_f32_fp4 v[18:19], v83, 1.0 op_sel:[1,0,0]
	v_pk_fma_f32 v[206:207], v[252:253], v[18:19], v[28:29] op_sel_hi:[0,1,1]
	v_cvt_scalef32_pk_f32_fp4 v[18:19], v83, 1.0 op_sel:[0,1,0]
	v_pk_fma_f32 v[204:205], v[252:253], v[18:19], v[30:31] op_sel_hi:[0,1,1]
	v_cvt_scalef32_pk_f32_fp4 v[18:19], v83, 1.0 op_sel:[1,1,0]
	v_pk_fma_f32 v[202:203], v[252:253], v[18:19], v[86:87] op_sel_hi:[0,1,1]
	v_cvt_scalef32_pk_f32_fp4 v[18:19], v84, 1.0
	v_pk_fma_f32 v[200:201], v[252:253], v[18:19], v[90:91] op_sel_hi:[0,1,1]
	v_cvt_scalef32_pk_f32_fp4 v[18:19], v84, 1.0 op_sel:[1,0,0]
	v_pk_fma_f32 v[198:199], v[252:253], v[18:19], v[94:95] op_sel_hi:[0,1,1]
	v_cvt_scalef32_pk_f32_fp4 v[18:19], v84, 1.0 op_sel:[0,1,0]
	v_pk_fma_f32 v[196:197], v[252:253], v[18:19], v[96:97] op_sel_hi:[0,1,1]
	v_cvt_scalef32_pk_f32_fp4 v[18:19], v84, 1.0 op_sel:[1,1,0]
	v_pk_fma_f32 v[194:195], v[252:253], v[18:19], v[98:99] op_sel_hi:[0,1,1]
	v_cvt_scalef32_pk_f32_fp4 v[18:19], v85, 1.0
	v_pk_fma_f32 v[192:193], v[252:253], v[18:19], v[100:101] op_sel_hi:[0,1,1]
	v_cvt_scalef32_pk_f32_fp4 v[18:19], v85, 1.0 op_sel:[1,0,0]
	v_pk_fma_f32 v[190:191], v[252:253], v[18:19], v[102:103] op_sel_hi:[0,1,1]
	v_cvt_scalef32_pk_f32_fp4 v[18:19], v85, 1.0 op_sel:[0,1,0]
	v_pk_fma_f32 v[188:189], v[252:253], v[18:19], v[104:105] op_sel_hi:[0,1,1]
	v_cvt_scalef32_pk_f32_fp4 v[18:19], v85, 1.0 op_sel:[1,1,0]
	v_pk_fma_f32 v[176:177], v[252:253], v[18:19], v[16:17] op_sel_hi:[0,1,1]
	v_lshl_add_u64 v[0:1], v[120:121], 0, v[0:1]
	v_lshl_add_u64 v[4:5], v[120:121], 0, v[4:5]
	global_load_dwordx4 v[110:113], v[0:1], off offset:768
	global_load_dwordx4 v[106:109], v[4:5], off offset:768
	v_lshl_add_u64 v[0:1], v[120:121], 0, v[2:3]
	v_lshl_add_u64 v[2:3], v[120:121], 0, v[8:9]
	global_load_dwordx4 v[102:105], v[0:1], off offset:768
	global_load_dwordx4 v[98:101], v[2:3], off offset:768
	v_lshl_add_u64 v[0:1], v[120:121], 0, v[6:7]
	v_lshl_add_u64 v[2:3], v[120:121], 0, v[12:13]
	global_load_dwordx4 v[94:97], v[0:1], off offset:768
	global_load_dwordx4 v[90:93], v[2:3], off offset:768
	v_lshl_add_u64 v[0:1], v[120:121], 0, v[10:11]
	v_lshl_add_u64 v[2:3], v[120:121], 0, v[14:15]
	global_load_dwordx4 v[86:89], v[0:1], off offset:768
	global_load_dwordx4 v[82:85], v[2:3], off offset:768
	s_addk_i32 s24, 0x200
	s_cmp_lg_u32 s24, s61
	s_cbranch_scc0 .LBB0_334
.LBB0_330:
	s_waitcnt vmcnt(22)
	v_cvt_scalef32_pk32_f32_fp6 v[0:31], v[32:37], 1.0
	v_pk_fma_f32 v[0:1], v[0:1], v[152:153], 0 op_sel_hi:[1,1,0]
	v_pk_fma_f32 v[2:3], v[2:3], v[170:171], 0 op_sel_hi:[1,1,0]
	v_pk_fma_f32 v[0:1], v[4:5], v[148:149], v[0:1]
	v_pk_fma_f32 v[2:3], v[6:7], v[172:173], v[2:3]
	v_pk_fma_f32 v[0:1], v[8:9], v[144:145], v[0:1]
	v_pk_fma_f32 v[2:3], v[10:11], v[174:175], v[2:3]
	v_pk_fma_f32 v[0:1], v[12:13], v[140:141], v[0:1]
	v_pk_fma_f32 v[2:3], v[14:15], v[178:179], v[2:3]
	v_pk_fma_f32 v[0:1], v[16:17], v[168:169], v[0:1]
	v_pk_fma_f32 v[2:3], v[18:19], v[180:181], v[2:3]
	v_pk_fma_f32 v[0:1], v[20:21], v[164:165], v[0:1]
	v_pk_fma_f32 v[2:3], v[22:23], v[182:183], v[2:3]
	v_pk_fma_f32 v[0:1], v[24:25], v[160:161], v[0:1]
	v_pk_fma_f32 v[2:3], v[26:27], v[184:185], v[2:3]
	v_pk_fma_f32 v[0:1], v[28:29], v[156:157], v[0:1]
	v_pk_fma_f32 v[2:3], v[30:31], v[186:187], v[2:3]
	v_add_f32_e32 v4, v2, v3
	v_add_f32_e32 v5, v0, v1
	v_add_f32_e32 v117, v4, v5
	s_waitcnt vmcnt(20)
	v_cvt_scalef32_pk32_f32_fp6 v[0:31], v[38:43], 1.0
	v_pk_fma_f32 v[0:1], v[0:1], v[152:153], 0 op_sel_hi:[1,1,0]
	v_pk_fma_f32 v[2:3], v[2:3], v[170:171], 0 op_sel_hi:[1,1,0]
	v_pk_fma_f32 v[0:1], v[4:5], v[148:149], v[0:1]
	v_pk_fma_f32 v[2:3], v[6:7], v[172:173], v[2:3]
	v_pk_fma_f32 v[0:1], v[8:9], v[144:145], v[0:1]
	v_pk_fma_f32 v[2:3], v[10:11], v[174:175], v[2:3]
	v_pk_fma_f32 v[0:1], v[12:13], v[140:141], v[0:1]
	v_pk_fma_f32 v[2:3], v[14:15], v[178:179], v[2:3]
	v_pk_fma_f32 v[0:1], v[16:17], v[168:169], v[0:1]
	v_pk_fma_f32 v[2:3], v[18:19], v[180:181], v[2:3]
	v_pk_fma_f32 v[0:1], v[20:21], v[164:165], v[0:1]
	v_pk_fma_f32 v[2:3], v[22:23], v[182:183], v[2:3]
	v_pk_fma_f32 v[0:1], v[24:25], v[160:161], v[0:1]
	v_pk_fma_f32 v[2:3], v[26:27], v[184:185], v[2:3]
	v_pk_fma_f32 v[0:1], v[28:29], v[156:157], v[0:1]
	v_pk_fma_f32 v[2:3], v[30:31], v[186:187], v[2:3]
	v_add_f32_e32 v4, v2, v3
	v_add_f32_e32 v5, v0, v1
	v_add_f32_e32 v131, v4, v5
	s_waitcnt vmcnt(18)
	v_cvt_scalef32_pk32_f32_fp6 v[0:31], v[44:49], 1.0
	v_pk_fma_f32 v[0:1], v[0:1], v[152:153], 0 op_sel_hi:[1,1,0]
	v_pk_fma_f32 v[2:3], v[2:3], v[170:171], 0 op_sel_hi:[1,1,0]
	v_pk_fma_f32 v[0:1], v[4:5], v[148:149], v[0:1]
	v_pk_fma_f32 v[2:3], v[6:7], v[172:173], v[2:3]
	v_pk_fma_f32 v[0:1], v[8:9], v[144:145], v[0:1]
	v_pk_fma_f32 v[2:3], v[10:11], v[174:175], v[2:3]
	v_pk_fma_f32 v[0:1], v[12:13], v[140:141], v[0:1]
	v_pk_fma_f32 v[2:3], v[14:15], v[178:179], v[2:3]
	v_pk_fma_f32 v[0:1], v[16:17], v[168:169], v[0:1]
	v_pk_fma_f32 v[2:3], v[18:19], v[180:181], v[2:3]
	v_pk_fma_f32 v[0:1], v[20:21], v[164:165], v[0:1]
	v_pk_fma_f32 v[2:3], v[22:23], v[182:183], v[2:3]
	v_pk_fma_f32 v[0:1], v[24:25], v[160:161], v[0:1]
	v_pk_fma_f32 v[2:3], v[26:27], v[184:185], v[2:3]
	v_pk_fma_f32 v[0:1], v[28:29], v[156:157], v[0:1]
	v_pk_fma_f32 v[2:3], v[30:31], v[186:187], v[2:3]
	v_add_f32_e32 v4, v2, v3
	v_add_f32_e32 v5, v0, v1
	v_add_f32_e32 v133, v4, v5
	s_waitcnt vmcnt(16)
	v_cvt_scalef32_pk32_f32_fp6 v[0:31], v[50:55], 1.0
	v_pk_fma_f32 v[0:1], v[0:1], v[152:153], 0 op_sel_hi:[1,1,0]
	v_pk_fma_f32 v[2:3], v[2:3], v[170:171], 0 op_sel_hi:[1,1,0]
	v_pk_fma_f32 v[0:1], v[4:5], v[148:149], v[0:1]
	v_pk_fma_f32 v[2:3], v[6:7], v[172:173], v[2:3]
	v_pk_fma_f32 v[0:1], v[8:9], v[144:145], v[0:1]
	v_pk_fma_f32 v[2:3], v[10:11], v[174:175], v[2:3]
	v_pk_fma_f32 v[0:1], v[12:13], v[140:141], v[0:1]
	v_pk_fma_f32 v[2:3], v[14:15], v[178:179], v[2:3]
	v_pk_fma_f32 v[0:1], v[16:17], v[168:169], v[0:1]
	v_pk_fma_f32 v[2:3], v[18:19], v[180:181], v[2:3]
	v_pk_fma_f32 v[0:1], v[20:21], v[164:165], v[0:1]
	v_pk_fma_f32 v[2:3], v[22:23], v[182:183], v[2:3]
	v_pk_fma_f32 v[0:1], v[24:25], v[160:161], v[0:1]
	v_pk_fma_f32 v[2:3], v[26:27], v[184:185], v[2:3]
	v_pk_fma_f32 v[0:1], v[28:29], v[156:157], v[0:1]
	v_pk_fma_f32 v[2:3], v[30:31], v[186:187], v[2:3]
	v_add_f32_e32 v4, v2, v3
	v_add_f32_e32 v5, v0, v1
	v_add_f32_e32 v218, v4, v5
	s_waitcnt vmcnt(14)
	v_cvt_scalef32_pk32_f32_fp6 v[0:31], v[56:61], 1.0
	v_pk_fma_f32 v[0:1], v[0:1], v[152:153], 0 op_sel_hi:[1,1,0]
	v_pk_fma_f32 v[2:3], v[2:3], v[170:171], 0 op_sel_hi:[1,1,0]
	v_pk_fma_f32 v[0:1], v[4:5], v[148:149], v[0:1]
	v_pk_fma_f32 v[2:3], v[6:7], v[172:173], v[2:3]
	v_pk_fma_f32 v[0:1], v[8:9], v[144:145], v[0:1]
	v_pk_fma_f32 v[2:3], v[10:11], v[174:175], v[2:3]
	v_pk_fma_f32 v[0:1], v[12:13], v[140:141], v[0:1]
	v_pk_fma_f32 v[2:3], v[14:15], v[178:179], v[2:3]
	v_pk_fma_f32 v[0:1], v[16:17], v[168:169], v[0:1]
	v_pk_fma_f32 v[2:3], v[18:19], v[180:181], v[2:3]
	v_pk_fma_f32 v[0:1], v[20:21], v[164:165], v[0:1]
	v_pk_fma_f32 v[2:3], v[22:23], v[182:183], v[2:3]
	v_pk_fma_f32 v[0:1], v[24:25], v[160:161], v[0:1]
	v_pk_fma_f32 v[2:3], v[26:27], v[184:185], v[2:3]
	v_pk_fma_f32 v[0:1], v[28:29], v[156:157], v[0:1]
	v_pk_fma_f32 v[2:3], v[30:31], v[186:187], v[2:3]
	v_add_f32_e32 v4, v2, v3
	v_add_f32_e32 v5, v0, v1
	v_add_f32_e32 v219, v4, v5
	s_waitcnt vmcnt(12)
	v_cvt_scalef32_pk32_f32_fp6 v[0:31], v[62:67], 1.0
	v_pk_fma_f32 v[0:1], v[0:1], v[152:153], 0 op_sel_hi:[1,1,0]
	v_pk_fma_f32 v[2:3], v[2:3], v[170:171], 0 op_sel_hi:[1,1,0]
	v_pk_fma_f32 v[0:1], v[4:5], v[148:149], v[0:1]
	v_pk_fma_f32 v[2:3], v[6:7], v[172:173], v[2:3]
	v_pk_fma_f32 v[0:1], v[8:9], v[144:145], v[0:1]
	v_pk_fma_f32 v[2:3], v[10:11], v[174:175], v[2:3]
	v_pk_fma_f32 v[0:1], v[12:13], v[140:141], v[0:1]
	v_pk_fma_f32 v[2:3], v[14:15], v[178:179], v[2:3]
	v_pk_fma_f32 v[0:1], v[16:17], v[168:169], v[0:1]
	v_pk_fma_f32 v[2:3], v[18:19], v[180:181], v[2:3]
	v_pk_fma_f32 v[0:1], v[20:21], v[164:165], v[0:1]
	v_pk_fma_f32 v[2:3], v[22:23], v[182:183], v[2:3]
	v_pk_fma_f32 v[0:1], v[24:25], v[160:161], v[0:1]
	v_pk_fma_f32 v[2:3], v[26:27], v[184:185], v[2:3]
	v_pk_fma_f32 v[0:1], v[28:29], v[156:157], v[0:1]
	v_pk_fma_f32 v[2:3], v[30:31], v[186:187], v[2:3]
	v_add_f32_e32 v4, v2, v3
	v_add_f32_e32 v5, v0, v1
	v_add_f32_e32 v246, v4, v5
	s_waitcnt vmcnt(10)
	v_cvt_scalef32_pk32_f32_fp6 v[0:31], v[68:73], 1.0
	v_pk_fma_f32 v[0:1], v[0:1], v[152:153], 0 op_sel_hi:[1,1,0]
	v_pk_fma_f32 v[2:3], v[2:3], v[170:171], 0 op_sel_hi:[1,1,0]
	v_pk_fma_f32 v[0:1], v[4:5], v[148:149], v[0:1]
	v_pk_fma_f32 v[2:3], v[6:7], v[172:173], v[2:3]
	v_pk_fma_f32 v[0:1], v[8:9], v[144:145], v[0:1]
	v_pk_fma_f32 v[2:3], v[10:11], v[174:175], v[2:3]
	v_pk_fma_f32 v[0:1], v[12:13], v[140:141], v[0:1]
	v_pk_fma_f32 v[2:3], v[14:15], v[178:179], v[2:3]
	v_pk_fma_f32 v[0:1], v[16:17], v[168:169], v[0:1]
	v_pk_fma_f32 v[2:3], v[18:19], v[180:181], v[2:3]
	v_pk_fma_f32 v[0:1], v[20:21], v[164:165], v[0:1]
	v_pk_fma_f32 v[2:3], v[22:23], v[182:183], v[2:3]
	v_pk_fma_f32 v[0:1], v[24:25], v[160:161], v[0:1]
	v_pk_fma_f32 v[2:3], v[26:27], v[184:185], v[2:3]
	v_pk_fma_f32 v[0:1], v[28:29], v[156:157], v[0:1]
	v_pk_fma_f32 v[2:3], v[30:31], v[186:187], v[2:3]
	v_add_f32_e32 v4, v2, v3
	v_add_f32_e32 v5, v0, v1
	v_add_f32_e32 v247, v4, v5
	s_waitcnt vmcnt(8)
	v_cvt_scalef32_pk32_f32_fp6 v[0:31], v[74:79], 1.0
	v_pk_fma_f32 v[0:1], v[0:1], v[152:153], 0 op_sel_hi:[1,1,0]
	v_pk_fma_f32 v[2:3], v[2:3], v[170:171], 0 op_sel_hi:[1,1,0]
	v_pk_fma_f32 v[0:1], v[4:5], v[148:149], v[0:1]
	v_pk_fma_f32 v[2:3], v[6:7], v[172:173], v[2:3]
	v_pk_fma_f32 v[0:1], v[8:9], v[144:145], v[0:1]
	v_pk_fma_f32 v[2:3], v[10:11], v[174:175], v[2:3]
	v_pk_fma_f32 v[0:1], v[12:13], v[140:141], v[0:1]
	v_pk_fma_f32 v[2:3], v[14:15], v[178:179], v[2:3]
	v_pk_fma_f32 v[0:1], v[16:17], v[168:169], v[0:1]
	v_pk_fma_f32 v[2:3], v[18:19], v[180:181], v[2:3]
	v_pk_fma_f32 v[0:1], v[20:21], v[164:165], v[0:1]
	v_pk_fma_f32 v[2:3], v[22:23], v[182:183], v[2:3]
	v_pk_fma_f32 v[0:1], v[24:25], v[160:161], v[0:1]
	v_pk_fma_f32 v[2:3], v[26:27], v[184:185], v[2:3]
	v_pk_fma_f32 v[0:1], v[28:29], v[156:157], v[0:1]
	v_pk_fma_f32 v[2:3], v[30:31], v[186:187], v[2:3]
	v_add_f32_e32 v4, v2, v3
	v_add_f32_e32 v5, v0, v1
	v_add_f32_e32 v1, v4, v5
	v_add_u32_e32 v8, s24, v239
	ds_read_b64 v[16:17], v8
	s_nop 1
	v_permlane16_swap_b32_e32 v117, v219
	v_permlane16_swap_b32_e32 v131, v246
	v_permlane16_swap_b32_e32 v133, v247
	v_permlane16_swap_b32_e32 v218, v1
	v_add_f32_e32 v117, v117, v219
	v_add_f32_e32 v131, v131, v246
	v_add_f32_e32 v133, v133, v247
	v_add_f32_e32 v218, v218, v1
	s_nop 1
	v_add_f32_dpp v117, v117, v117 row_ror:8 row_mask:0xf bank_mask:0x3
	v_add_f32_dpp v117, v133, v133 row_ror:8 row_mask:0xf bank_mask:0xc
	v_add_f32_dpp v131, v131, v131 row_ror:8 row_mask:0xf bank_mask:0x3
	v_add_f32_dpp v131, v218, v218 row_ror:8 row_mask:0xf bank_mask:0xc
	s_nop 1
	v_add_f32_dpp v117, v117, v117 row_ror:12 row_mask:0xf bank_mask:0x5
	v_add_f32_dpp v117, v131, v131 row_ror:4 row_mask:0xf bank_mask:0xa
	s_nop 1
	v_add_f32_dpp v117, v117, v117 quad_perm:[2,3,0,1] row_mask:0xf bank_mask:0xf
	s_nop 1
	v_add_f32_dpp v1, v117, v117 quad_perm:[1,0,3,2] row_mask:0xf bank_mask:0xf
	s_waitcnt lgkmcnt(0)
	v_mul_f32_e32 v18, 0x3caaaaab, v1
	v_mul_f32_e32 v16, 0x3f3504f3, v18
	v_cmp_nlt_f32_e64 s[2:3], |v16|, 1.0
	s_and_saveexec_b64 s[26:27], s[2:3]
	s_xor_b64 s[2:3], exec, s[26:27]
	s_cbranch_execz .LBB0_332
	s_mov_b32 s25, 0x378e98ab
	v_fma_f32 v1, |v16|, s25, v233
	s_mov_b32 s25, 0x3b7cd369
	v_fma_f32 v1, |v16|, v1, s25
	s_mov_b32 s25, 0xbcc618b2
	v_fma_f32 v1, |v16|, v1, s25
	s_mov_b32 s25, 0x3dda74e4
	v_fma_f32 v1, |v16|, v1, s25
	s_mov_b32 s25, 0x3f228afd
	v_fma_f32 v1, |v16|, v1, s25
	s_mov_b32 s25, 0x3e03c728
	v_fma_f32 v1, |v16|, v1, s25
	v_fma_f32 v1, |v16|, v1, |v16|
	v_mul_f32_e32 v4, 0xbfb8aa3b, v1
	s_mov_b32 s25, 0xbfb8aa3b
	v_fma_f32 v5, v1, s25, -v4
	v_rndne_f32_e32 v8, v4
	v_fmac_f32_e32 v5, 0xb2a5705f, v1
	v_sub_f32_e32 v4, v4, v8
	v_add_f32_e32 v4, v4, v5
	v_cvt_i32_f32_e32 v5, v8
	v_exp_f32_e32 v4, v4
	s_mov_b32 s25, 0x42ce8ed0
	v_cmp_nlt_f32_e32 vcc, s25, v1
	s_mov_b32 s25, 0xc2b17218
	v_ldexp_f32 v4, v4, v5
	v_cndmask_b32_e32 v4, 0, v4, vcc
	v_cmp_ngt_f32_e32 vcc, s25, v1
	s_nop 1
	v_cndmask_b32_e32 v1, v234, v4, vcc
	v_sub_f32_e32 v19, 1.0, v1
